# v18 plus retention key loop: counted LDS waits in front of the four p0 MFMAs instead of one full wait
# baseline (speedup 1.0000x reference)
.LBB0_232:
	s_mul_i32 s66, s60, 0x5000
	s_add_i32 s0, s66, 0
	v_add_u32_e32 v36, s0, v144
	s_waitcnt vmcnt(2)
	s_barrier
	v_add_u32_e32 v32, v36, v151
	ds_read_b128 v[48:51], v32
	ds_read_b128 v[32:35], v32 offset:4096
	v_add_u32_e32 v37, v36, v145
	ds_read_b128 v[64:67], v37
	ds_read_b128 v[52:55], v37 offset:4096
	v_add_u32_e32 v37, v36, v146
	v_add_u32_e32 v36, v36, v147
	ds_read_b128 v[68:71], v37
	ds_read_b128 v[56:59], v37 offset:4096
	ds_read_b128 v[72:75], v36
	ds_read_b128 v[60:63], v36 offset:4096
	s_waitcnt lgkmcnt(6)
	v_mfma_f32_32x32x16_bf16 v[32:47], v[32:35], v[94:97], 0
	s_waitcnt lgkmcnt(4)
	v_mfma_f32_32x32x16_bf16 v[32:47], v[52:55], v[90:93], v[32:47]
	v_add3_u32 v52, s0, v117, v143
	v_add_u32_e32 v153, v52, v142
	ds_read_b64_tr_b16 v[110:111], v153 offset:12288
	ds_read_b64_tr_b16 v[112:113], v153 offset:12800
	ds_read_b64_tr_b16 v[106:107], v153 offset:13312
	ds_read_b64_tr_b16 v[108:109], v153 offset:13824
	ds_read_b64_tr_b16 v[102:103], v153 offset:14336
	ds_read_b64_tr_b16 v[104:105], v153 offset:14848
	ds_read_b64_tr_b16 v[98:99], v153 offset:15360
	ds_read_b64_tr_b16 v[100:101], v153 offset:15872
	s_add_i32 s0, s41, 63
	s_cmp_ge_u32 s0, s33
	s_cselect_b64 s[58:59], -1, 0
	s_cmp_lt_u32 s0, s33
	s_waitcnt lgkmcnt(10)
	v_mfma_f32_32x32x16_bf16 v[32:47], v[56:59], v[86:89], v[32:47]
	s_cselect_b64 s[62:63], -1, 0
	s_cmp_gt_u32 s41, s50
	s_cselect_b64 s[72:73], -1, 0
	s_or_b64 s[72:73], s[62:63], s[72:73]
	s_mov_b64 s[62:63], -1
	s_andn2_b64 vcc, exec, s[72:73]
	s_waitcnt lgkmcnt(8)
	v_mfma_f32_32x32x16_bf16 v[32:47], v[60:63], v[82:85], v[32:47]
	v_mfma_f32_32x32x16_bf16 v[48:63], v[48:51], v[94:97], 0
	v_mfma_f32_32x32x16_bf16 v[48:63], v[64:67], v[90:93], v[48:63]
	v_mfma_f32_32x32x16_bf16 v[48:63], v[68:71], v[86:89], v[48:63]
	v_mfma_f32_32x32x16_bf16 v[48:63], v[72:75], v[82:85], v[48:63]
	s_cbranch_vccz .LBB0_235
	v_cvt_f32_i32_e32 v64, v152
	s_mov_b32 s0, 0xc2000000
	v_cmp_lt_f32_e32 vcc, 0, v64
	v_add_f32_e32 v65, -1.0, v64
	s_mov_b32 s62, -2.0
	v_cndmask_b32_e32 v66, v137, v115, vcc
	v_mul_f32_e64 v66, |v64|, v66
	v_cmp_lt_f32_e32 vcc, 0, v65
	v_exp_f32_e32 v155, v66
	s_mov_b32 s63, 0xc0400000
	v_cndmask_b32_e32 v66, v137, v115, vcc
	v_mul_f32_e64 v66, |v65|, v66
	v_exp_f32_e32 v156, v66
	v_pk_add_f32 v[66:67], v[64:65], s[0:1] op_sel_hi:[1,0]
	s_nop 0
	v_cmp_lt_f32_e32 vcc, 0, v66
	s_nop 1
	v_cndmask_b32_e32 v68, v137, v115, vcc
	v_cmp_lt_f32_e32 vcc, 0, v67
	v_mul_f32_e64 v68, |v66|, v68
	v_exp_f32_e32 v68, v68
	v_cndmask_b32_e32 v69, v137, v115, vcc
	v_mul_f32_e64 v69, |v67|, v69
	v_exp_f32_e32 v69, v69
	v_cmp_neq_f32_e32 vcc, 0, v67
	s_nop 1
	v_cndmask_b32_e32 v67, 2.0, v69, vcc
	v_cmp_neq_f32_e32 vcc, 0, v66
	s_nop 1
	v_cndmask_b32_e32 v66, 2.0, v68, vcc
	v_pk_mul_f32 v[122:123], v[32:33], v[66:67]
	v_pk_add_f32 v[66:67], v[64:65], s[62:63] op_sel_hi:[0,1]
	v_cmp_lt_f32_e32 vcc, 0, v66
	s_mov_b32 s62, 0xc1000000
	s_mov_b32 s63, 0xc1100000
	v_cndmask_b32_e32 v68, v137, v115, vcc
	v_mul_f32_e64 v68, |v66|, v68
	v_cmp_lt_f32_e32 vcc, 0, v67
	v_exp_f32_e32 v157, v68
	s_nop 0
	v_cndmask_b32_e32 v68, v137, v115, vcc
	v_mul_f32_e64 v68, |v67|, v68
	v_exp_f32_e32 v158, v68
	v_pk_add_f32 v[68:69], v[66:67], s[0:1] op_sel_hi:[1,0]
	s_nop 0
	v_cmp_lt_f32_e32 vcc, 0, v68
	s_nop 1
	v_cndmask_b32_e32 v70, v137, v115, vcc
	v_cmp_lt_f32_e32 vcc, 0, v69
	v_mul_f32_e64 v70, |v68|, v70
	v_exp_f32_e32 v70, v70
	v_cndmask_b32_e32 v71, v137, v115, vcc
	v_mul_f32_e64 v71, |v69|, v71
	v_exp_f32_e32 v71, v71
	v_cmp_neq_f32_e32 vcc, 0, v69
	s_nop 1
	v_cndmask_b32_e32 v69, 2.0, v71, vcc
	v_cmp_neq_f32_e32 vcc, 0, v68
	s_nop 1
	v_cndmask_b32_e32 v68, 2.0, v70, vcc
	v_pk_mul_f32 v[124:125], v[34:35], v[68:69]
	v_pk_add_f32 v[68:69], v[64:65], s[62:63] op_sel_hi:[0,1]
	v_cmp_lt_f32_e32 vcc, 0, v68
	s_mov_b32 s62, 0xc1200000
	s_mov_b32 s63, 0xc1300000
	v_cndmask_b32_e32 v70, v137, v115, vcc
	v_mul_f32_e64 v70, |v68|, v70
	v_cmp_lt_f32_e32 vcc, 0, v69
	v_exp_f32_e32 v159, v70
	s_nop 0
	v_cndmask_b32_e32 v70, v137, v115, vcc
	v_mul_f32_e64 v70, |v69|, v70
	v_exp_f32_e32 v160, v70
	v_pk_add_f32 v[70:71], v[68:69], s[0:1] op_sel_hi:[1,0]
	s_nop 0
	v_cmp_lt_f32_e32 vcc, 0, v70
	s_nop 1
	v_cndmask_b32_e32 v72, v137, v115, vcc
	v_cmp_lt_f32_e32 vcc, 0, v71
	v_mul_f32_e64 v72, |v70|, v72
	v_exp_f32_e32 v72, v72
	v_cndmask_b32_e32 v73, v137, v115, vcc
	v_mul_f32_e64 v73, |v71|, v73
	v_exp_f32_e32 v73, v73
	v_cmp_neq_f32_e32 vcc, 0, v71
	s_nop 1
	v_cndmask_b32_e32 v71, 2.0, v73, vcc
	v_cmp_neq_f32_e32 vcc, 0, v70
	s_nop 1
	v_cndmask_b32_e32 v70, 2.0, v72, vcc
	v_pk_mul_f32 v[126:127], v[36:37], v[70:71]
	v_pk_add_f32 v[70:71], v[64:65], s[62:63] op_sel_hi:[0,1]
	v_cmp_lt_f32_e32 vcc, 0, v70
	s_mov_b32 s62, 0xc1800000
	s_mov_b32 s63, 0xc1880000
	v_cndmask_b32_e32 v72, v137, v115, vcc
	v_mul_f32_e64 v72, |v70|, v72
	v_cmp_lt_f32_e32 vcc, 0, v71
	v_exp_f32_e32 v161, v72
	s_nop 0
	v_cndmask_b32_e32 v72, v137, v115, vcc
	v_mul_f32_e64 v72, |v71|, v72
	v_exp_f32_e32 v162, v72
	v_pk_add_f32 v[72:73], v[70:71], s[0:1] op_sel_hi:[1,0]
	s_nop 0
	v_cmp_lt_f32_e32 vcc, 0, v72
	s_nop 1
	v_cndmask_b32_e32 v74, v137, v115, vcc
	v_cmp_lt_f32_e32 vcc, 0, v73
	v_mul_f32_e64 v74, |v72|, v74
	v_exp_f32_e32 v74, v74
	v_cndmask_b32_e32 v75, v137, v115, vcc
	v_mul_f32_e64 v75, |v73|, v75
	v_exp_f32_e32 v75, v75
	v_cmp_neq_f32_e32 vcc, 0, v73
	s_nop 1
	v_cndmask_b32_e32 v73, 2.0, v75, vcc
	v_cmp_neq_f32_e32 vcc, 0, v72
	s_nop 1
	v_cndmask_b32_e32 v72, 2.0, v74, vcc
	v_pk_mul_f32 v[128:129], v[38:39], v[72:73]
	v_pk_add_f32 v[72:73], v[64:65], s[62:63] op_sel_hi:[0,1]
	v_cmp_lt_f32_e32 vcc, 0, v72
	s_mov_b32 s62, 0xc1900000
	s_mov_b32 s63, 0xc1980000
	v_cndmask_b32_e32 v74, v137, v115, vcc
	v_mul_f32_e64 v74, |v72|, v74
	v_cmp_lt_f32_e32 vcc, 0, v73
	v_exp_f32_e32 v163, v74
	s_nop 0
	v_cndmask_b32_e32 v74, v137, v115, vcc
	v_mul_f32_e64 v74, |v73|, v74
	v_exp_f32_e32 v164, v74
	v_pk_add_f32 v[74:75], v[72:73], s[0:1] op_sel_hi:[1,0]
	s_nop 0
	v_cmp_lt_f32_e32 vcc, 0, v74
	s_nop 1
	v_cndmask_b32_e32 v76, v137, v115, vcc
	v_cmp_lt_f32_e32 vcc, 0, v75
	v_mul_f32_e64 v76, |v74|, v76
	v_exp_f32_e32 v76, v76
	v_cndmask_b32_e32 v77, v137, v115, vcc
	v_mul_f32_e64 v77, |v75|, v77
	v_exp_f32_e32 v77, v77
	v_cmp_neq_f32_e32 vcc, 0, v75
	s_nop 1
	v_cndmask_b32_e32 v75, 2.0, v77, vcc
	v_cmp_neq_f32_e32 vcc, 0, v74
	s_nop 1
	v_cndmask_b32_e32 v74, 2.0, v76, vcc
	v_pk_mul_f32 v[130:131], v[40:41], v[74:75]
	v_pk_add_f32 v[74:75], v[64:65], s[62:63] op_sel_hi:[0,1]
	v_cmp_lt_f32_e32 vcc, 0, v74
	s_mov_b32 s62, 0xc1c00000
	s_mov_b32 s63, 0xc1c80000
	v_cndmask_b32_e32 v76, v137, v115, vcc
	v_mul_f32_e64 v76, |v74|, v76
	v_cmp_lt_f32_e32 vcc, 0, v75
	v_exp_f32_e32 v165, v76
	s_nop 0
	v_cndmask_b32_e32 v76, v137, v115, vcc
	v_mul_f32_e64 v76, |v75|, v76
	v_exp_f32_e32 v166, v76
	v_pk_add_f32 v[76:77], v[74:75], s[0:1] op_sel_hi:[1,0]
	s_nop 0
	v_cmp_lt_f32_e32 vcc, 0, v76
	s_nop 1
	v_cndmask_b32_e32 v78, v137, v115, vcc
	v_cmp_lt_f32_e32 vcc, 0, v77
	v_mul_f32_e64 v78, |v76|, v78
	v_exp_f32_e32 v78, v78
	v_cndmask_b32_e32 v79, v137, v115, vcc
	v_mul_f32_e64 v79, |v77|, v79
	v_exp_f32_e32 v79, v79
	v_cmp_neq_f32_e32 vcc, 0, v77
	s_nop 1
	v_cndmask_b32_e32 v77, 2.0, v79, vcc
	v_cmp_neq_f32_e32 vcc, 0, v76
	s_nop 1
	v_cndmask_b32_e32 v76, 2.0, v78, vcc
	v_pk_mul_f32 v[132:133], v[42:43], v[76:77]
	v_pk_add_f32 v[76:77], v[64:65], s[62:63] op_sel_hi:[0,1]
	v_cmp_lt_f32_e32 vcc, 0, v76
	s_mov_b32 s62, 0xc1d00000
	s_mov_b32 s63, 0xc1d80000
	v_cndmask_b32_e32 v78, v137, v115, vcc
	v_mul_f32_e64 v78, |v76|, v78
	v_cmp_lt_f32_e32 vcc, 0, v77
	v_exp_f32_e32 v167, v78
	s_nop 0
	v_cndmask_b32_e32 v78, v137, v115, vcc
	v_mul_f32_e64 v78, |v77|, v78
	v_exp_f32_e32 v168, v78
	v_pk_add_f32 v[78:79], v[76:77], s[0:1] op_sel_hi:[1,0]
	s_nop 0
	v_cmp_lt_f32_e32 vcc, 0, v78
	s_nop 1
	v_cndmask_b32_e32 v134, v137, v115, vcc
	v_cmp_lt_f32_e32 vcc, 0, v79
	v_mul_f32_e64 v134, |v78|, v134
	v_exp_f32_e32 v134, v134
	v_cndmask_b32_e32 v135, v137, v115, vcc
	v_mul_f32_e64 v135, |v79|, v135
	v_exp_f32_e32 v135, v135
	v_cmp_neq_f32_e32 vcc, 0, v79
	s_nop 1
	v_cndmask_b32_e32 v79, 2.0, v135, vcc
	v_cmp_neq_f32_e32 vcc, 0, v78
	s_nop 1
	v_cndmask_b32_e32 v78, 2.0, v134, vcc
	v_pk_mul_f32 v[134:135], v[44:45], v[78:79]
	v_pk_add_f32 v[78:79], v[64:65], s[62:63] op_sel_hi:[0,1]
	v_add_f32_e32 v154, 0xc2000000, v78
	v_cmp_lt_f32_e32 vcc, 0, v78
	s_nop 1
	v_cndmask_b32_e32 v169, v137, v115, vcc
	v_cmp_lt_f32_e32 vcc, 0, v154
	v_mul_f32_e64 v169, |v78|, v169
	v_exp_f32_e32 v169, v169
	v_cndmask_b32_e32 v170, v137, v115, vcc
	v_mul_f32_e64 v170, |v154|, v170
	v_exp_f32_e32 v170, v170
	v_cmp_lt_f32_e32 vcc, 0, v79
	s_nop 1
	v_cndmask_b32_e32 v171, v137, v115, vcc
	v_mul_f32_e64 v171, |v79|, v171
	v_exp_f32_e32 v171, v171
	v_cmp_neq_f32_e32 vcc, 0, v154
	s_nop 1
	v_cndmask_b32_e32 v154, 2.0, v170, vcc
	v_add_f32_e32 v170, 0xc2000000, v79
	v_cmp_lt_f32_e32 vcc, 0, v170
	v_mul_f32_e32 v154, v46, v154
	s_nop 0
	v_cndmask_b32_e32 v172, v137, v115, vcc
	v_cmp_neq_f32_e32 vcc, 0, v79
	v_mul_f32_e64 v172, |v170|, v172
	v_exp_f32_e32 v172, v172
	v_cndmask_b32_e32 v79, 2.0, v171, vcc
	v_cmp_neq_f32_e32 vcc, 0, v78
	s_nop 1
	v_cndmask_b32_e32 v78, 2.0, v169, vcc
	v_cmp_neq_f32_e32 vcc, 0, v77
	s_nop 1
	v_cndmask_b32_e32 v77, 2.0, v168, vcc
	v_cmp_neq_f32_e32 vcc, 0, v76
	s_nop 1
	v_cndmask_b32_e32 v76, 2.0, v167, vcc
	v_cmp_neq_f32_e32 vcc, 0, v75
	s_nop 1
	v_cndmask_b32_e32 v75, 2.0, v166, vcc
	v_cmp_neq_f32_e32 vcc, 0, v74
	s_nop 1
	v_cndmask_b32_e32 v74, 2.0, v165, vcc
	v_cmp_neq_f32_e32 vcc, 0, v73
	s_nop 1
	v_cndmask_b32_e32 v73, 2.0, v164, vcc
	v_cmp_neq_f32_e32 vcc, 0, v72
	s_nop 1
	v_cndmask_b32_e32 v72, 2.0, v163, vcc
	v_cmp_neq_f32_e32 vcc, 0, v71
	s_nop 1
	v_cndmask_b32_e32 v71, 2.0, v162, vcc
	v_cmp_neq_f32_e32 vcc, 0, v70
	s_nop 1
	v_cndmask_b32_e32 v70, 2.0, v161, vcc
	v_cmp_neq_f32_e32 vcc, 0, v69
	s_nop 1
	v_cndmask_b32_e32 v69, 2.0, v160, vcc
	v_cmp_neq_f32_e32 vcc, 0, v68
	s_nop 1
	v_cndmask_b32_e32 v68, 2.0, v159, vcc
	v_cmp_neq_f32_e32 vcc, 0, v67
	s_nop 1
	v_cndmask_b32_e32 v67, 2.0, v158, vcc
	v_cmp_neq_f32_e32 vcc, 0, v66
	s_nop 1
	v_cndmask_b32_e32 v66, 2.0, v157, vcc
	v_cmp_neq_f32_e32 vcc, 0, v64
	s_nop 1
	v_cndmask_b32_e32 v64, 2.0, v155, vcc
	v_cmp_neq_f32_e32 vcc, 0, v65
	s_nop 1
	v_cndmask_b32_e32 v65, 2.0, v156, vcc
	v_cmp_neq_f32_e32 vcc, 0, v170
	s_nop 1
	v_cndmask_b32_e32 v155, 2.0, v172, vcc
	s_cbranch_execz .LBB0_236
